# first grid barrier: census loads issued together (was 16 serial L2 round trips); on top of P5 load batching + scan loader vmcnt
# speedup vs baseline: 1.0027x; 1.0027x over previous
.LBB0_57:
	v_readlane_b32 s4, v252, 34
	v_readlane_b32 s5, v252, 35
	s_mov_b64 s[28:29], -1
	s_nop 4
	global_load_dword v2, v18, s[4:5] sc1
	v_readlane_b32 s4, v252, 36
	v_readlane_b32 s5, v252, 37
	s_nop 4
	global_load_dword v3, v18, s[4:5] sc1
	v_readlane_b32 s4, v252, 38
	v_readlane_b32 s5, v252, 39
	s_nop 4
	global_load_dword v4, v18, s[4:5] sc1
	v_readlane_b32 s4, v252, 40
	v_readlane_b32 s5, v252, 41
	s_nop 4
	global_load_dword v5, v18, s[4:5] sc1
	v_readlane_b32 s4, v252, 42
	v_readlane_b32 s5, v252, 43
	s_nop 4
	global_load_dword v6, v18, s[4:5] sc1
	v_readlane_b32 s4, v252, 44
	v_readlane_b32 s5, v252, 45
	s_nop 4
	global_load_dword v7, v18, s[4:5] sc1
	v_readlane_b32 s4, v252, 46
	v_readlane_b32 s5, v252, 47
	s_nop 4
	global_load_dword v8, v18, s[4:5] sc1
	v_readlane_b32 s4, v252, 48
	v_readlane_b32 s5, v252, 49
	s_nop 4
	global_load_dword v9, v18, s[4:5] sc1
	v_readlane_b32 s4, v252, 50
	v_readlane_b32 s5, v252, 51
	s_nop 4
	global_load_dword v10, v18, s[4:5] sc1
	v_readlane_b32 s4, v252, 52
	v_readlane_b32 s5, v252, 53
	s_nop 4
	global_load_dword v11, v18, s[4:5] sc1
	v_readlane_b32 s4, v252, 54
	v_readlane_b32 s5, v252, 55
	s_nop 4
	global_load_dword v12, v18, s[4:5] sc1
	v_readlane_b32 s4, v252, 56
	v_readlane_b32 s5, v252, 57
	s_nop 4
	global_load_dword v13, v18, s[4:5] sc1
	v_readlane_b32 s4, v252, 58
	v_readlane_b32 s5, v252, 59
	s_nop 4
	global_load_dword v14, v18, s[4:5] sc1
	v_readlane_b32 s4, v252, 60
	v_readlane_b32 s5, v252, 61
	s_nop 4
	global_load_dword v15, v18, s[4:5] sc1
	v_readlane_b32 s4, v252, 62
	v_readlane_b32 s5, v252, 63
	s_nop 4
	global_load_dword v16, v18, s[4:5] sc1
	v_readlane_b32 s4, v251, 0
	v_readlane_b32 s5, v251, 1
	s_nop 4
	global_load_dword v17, v18, s[4:5] sc1
	s_mov_b64 s[4:5], -1
	s_waitcnt vmcnt(0)
	v_add_u32_e32 v19, v3, v2
	v_add_u32_e32 v19, v19, v4
	v_add_u32_e32 v19, v19, v5
	v_add_u32_e32 v19, v19, v6
	v_add_u32_e32 v19, v19, v7
	v_add_u32_e32 v19, v19, v8
	v_add_u32_e32 v19, v19, v9
	v_add_u32_e32 v19, v19, v10
	v_add_u32_e32 v19, v19, v11
	v_add_u32_e32 v19, v19, v12
	v_add_u32_e32 v19, v19, v13
	v_add_u32_e32 v19, v19, v14
	v_add_u32_e32 v19, v19, v15
	v_add_u32_e32 v19, v19, v16
	v_add_u32_e32 v19, v19, v17
	v_cmp_eq_u32_e32 vcc, s2, v19
	s_cbranch_vccnz .LBB0_56
	s_and_b32 s4, s3, 0xff
	s_cmp_eq_u32 s4, 0
	s_mov_b64 s[4:5], -1
	s_mov_b64 s[30:31], -1
	s_sleep 1
	s_cbranch_scc0 .LBB0_61
	v_readlane_b32 s4, v252, 32
	v_readlane_b32 s5, v252, 33
	s_nop 4
	global_load_dword v19, v18, s[4:5] sc1
	s_waitcnt vmcnt(0)
	v_cmp_eq_u32_e32 vcc, 0, v19
	s_cbranch_vccnz .LBB0_63
	s_mov_b64 s[30:31], 0
	s_mov_b64 s[4:5], -1
